# cross-half row-max exchange in the DA and MLA loops via v_permlane32_swap instead of an LDS bpermute round trip
# speedup vs baseline: 1.0066x; 1.0066x over previous
; DI float shx(float v, int mask, int lane) { return __builtin_bit_cast(float, __builtin_amdgcn_ds_bpermute((lane ^ mask) << 2, __builtin_bit_cast(int, v))); }
; DI float ex2(float x) { return __builtin_amdgcn_exp2f(x); }
; template <int MODE>
; DI void attn_unit(LAS unsigned char* lds, const bf16_t* Qg, int ldq, const bf16_t* Kg, int ldk, const bf16_t* VTg, int ldvt, bf16_t* Og, int ldo,
;                   int q0, int NT, const float* gout, const float* relb, float lam, float osc, const float* qgain) {
;     ...
;                 float mx = __builtin_fmaxf(__builtin_fmaxf(p0[0], p0[1]), p0[2]);
; #pragma unroll
;                 for (int i = 3; i < 15; i += 2) mx = __builtin_fmaxf(__builtin_fmaxf(mx, p0[i]), p0[i + 1]);
;                 mx = __builtin_fmaxf(mx, p0[15]);
; #pragma unroll
;                 for (int i = 0; i < 16; i += 2) mx = __builtin_fmaxf(__builtin_fmaxf(mx, p1[i]), p1[i + 1]);
;                 mx = __builtin_fmaxf(mx, shx(mx, 32, lane));
;                 if (t == 0 || __any(mx > 8.f)) {
;                     const float dl = (t == 0) ? mx : __builtin_fmaxf(mx, 0.f);
;                     mhat += dl;
; #pragma unroll
;                     for (int i = 0; i < 16; ++i) { p0[i] -= dl; p1[i] -= dl; }
; #pragma unroll
;                     for (int i = 0; i < 16; ++i) negm[i] = c15 - mhat;
;                     if (t > 0) { const float f = ex2(-dl); lrun *= f;
; #pragma unroll
;                         for (int d = 0; d < NDB; ++d)
; #pragma unroll
;                             for (int i = 0; i < 16; ++i) o[d][i] *= f; }
;                 }
.LBB0_193:
	s_nop 7
	v_max_f32_e32 v0, v84, v85
	v_max3_f32 v0, v0, v86, v87
	v_max3_f32 v0, v0, v88, v89
	v_max3_f32 v0, v0, v90, v91
	v_max3_f32 v0, v0, v92, v93
	v_max3_f32 v0, v0, v94, v95
	v_max3_f32 v0, v0, v96, v97
	v_max3_f32 v0, v0, v98, v99
	v_max3_f32 v0, v0, v100, v101
	v_max3_f32 v0, v0, v102, v103
	v_max3_f32 v0, v0, v104, v105
	v_max3_f32 v0, v0, v106, v107
	v_max3_f32 v0, v0, v108, v109
	v_max3_f32 v0, v0, v110, v111
	v_max3_f32 v0, v0, v112, v113
	v_max3_f32 v0, v0, v114, v115
	v_mov_b32_e32 v162, v0
	v_mov_b32_e32 v163, v0
	s_mov_b32 s2, 0x41000000
	s_nop 0
	v_permlane32_swap_b32_e32 v162, v163
	v_max3_f32 v0, v0, v162, v163
	v_cmp_lt_f32_e32 vcc, s2, v0
	s_cbranch_vccz .LBB0_195
	v_max_f32_e32 v0, v0, v0
	v_max_f32_e32 v0, 0, v0
	v_exp_f32_e64 v70, -v0
	v_add_f32_e32 v152, v152, v0
	v_sub_f32_e32 v68, v66, v152
	v_pk_add_f32 v[100:101], v[100:101], v[0:1] op_sel_hi:[1,0] neg_lo:[0,1] neg_hi:[0,1]
	v_pk_add_f32 v[102:103], v[102:103], v[0:1] op_sel_hi:[1,0] neg_lo:[0,1] neg_hi:[0,1]
	v_pk_add_f32 v[104:105], v[104:105], v[0:1] op_sel_hi:[1,0] neg_lo:[0,1] neg_hi:[0,1]
	v_pk_add_f32 v[106:107], v[106:107], v[0:1] op_sel_hi:[1,0] neg_lo:[0,1] neg_hi:[0,1]
	v_pk_add_f32 v[108:109], v[108:109], v[0:1] op_sel_hi:[1,0] neg_lo:[0,1] neg_hi:[0,1]
	v_pk_add_f32 v[110:111], v[110:111], v[0:1] op_sel_hi:[1,0] neg_lo:[0,1] neg_hi:[0,1]
	v_pk_add_f32 v[112:113], v[112:113], v[0:1] op_sel_hi:[1,0] neg_lo:[0,1] neg_hi:[0,1]
	v_pk_add_f32 v[114:115], v[114:115], v[0:1] op_sel_hi:[1,0] neg_lo:[0,1] neg_hi:[0,1]
	v_pk_add_f32 v[84:85], v[84:85], v[0:1] op_sel_hi:[1,0] neg_lo:[0,1] neg_hi:[0,1]
	v_pk_add_f32 v[86:87], v[86:87], v[0:1] op_sel_hi:[1,0] neg_lo:[0,1] neg_hi:[0,1]
	v_pk_add_f32 v[88:89], v[88:89], v[0:1] op_sel_hi:[1,0] neg_lo:[0,1] neg_hi:[0,1]
	v_pk_add_f32 v[90:91], v[90:91], v[0:1] op_sel_hi:[1,0] neg_lo:[0,1] neg_hi:[0,1]
	v_pk_add_f32 v[92:93], v[92:93], v[0:1] op_sel_hi:[1,0] neg_lo:[0,1] neg_hi:[0,1]
	v_pk_add_f32 v[94:95], v[94:95], v[0:1] op_sel_hi:[1,0] neg_lo:[0,1] neg_hi:[0,1]
	v_pk_add_f32 v[96:97], v[96:97], v[0:1] op_sel_hi:[1,0] neg_lo:[0,1] neg_hi:[0,1]
	v_pk_add_f32 v[98:99], v[98:99], v[0:1] op_sel_hi:[1,0] neg_lo:[0,1] neg_hi:[0,1]
	v_pk_mul_f32 v[64:65], v[64:65], v[70:71] op_sel_hi:[1,0]
	v_pk_mul_f32 v[62:63], v[62:63], v[70:71] op_sel_hi:[1,0]
	v_pk_mul_f32 v[60:61], v[60:61], v[70:71] op_sel_hi:[1,0]
	v_pk_mul_f32 v[58:59], v[58:59], v[70:71] op_sel_hi:[1,0]
	v_pk_mul_f32 v[56:57], v[56:57], v[70:71] op_sel_hi:[1,0]
	v_pk_mul_f32 v[54:55], v[54:55], v[70:71] op_sel_hi:[1,0]
	v_pk_mul_f32 v[52:53], v[52:53], v[70:71] op_sel_hi:[1,0]
	v_pk_mul_f32 v[50:51], v[50:51], v[70:71] op_sel_hi:[1,0]
	v_pk_mul_f32 v[48:49], v[48:49], v[70:71] op_sel_hi:[1,0]
	v_pk_mul_f32 v[46:47], v[46:47], v[70:71] op_sel_hi:[1,0]
	v_pk_mul_f32 v[44:45], v[44:45], v[70:71] op_sel_hi:[1,0]
	v_pk_mul_f32 v[42:43], v[42:43], v[70:71] op_sel_hi:[1,0]
	v_pk_mul_f32 v[40:41], v[40:41], v[70:71] op_sel_hi:[1,0]
	v_pk_mul_f32 v[38:39], v[38:39], v[70:71] op_sel_hi:[1,0]
	v_pk_mul_f32 v[36:37], v[36:37], v[70:71] op_sel_hi:[1,0]
	v_pk_mul_f32 v[34:35], v[34:35], v[70:71] op_sel_hi:[1,0]
	v_pk_mul_f32 v[32:33], v[32:33], v[70:71] op_sel_hi:[1,0]
	v_pk_mul_f32 v[30:31], v[30:31], v[70:71] op_sel_hi:[1,0]
	v_pk_mul_f32 v[28:29], v[28:29], v[70:71] op_sel_hi:[1,0]
	v_pk_mul_f32 v[26:27], v[26:27], v[70:71] op_sel_hi:[1,0]
	v_pk_mul_f32 v[24:25], v[24:25], v[70:71] op_sel_hi:[1,0]
	v_pk_mul_f32 v[22:23], v[22:23], v[70:71] op_sel_hi:[1,0]
	v_pk_mul_f32 v[20:21], v[20:21], v[70:71] op_sel_hi:[1,0]
	v_pk_mul_f32 v[18:19], v[18:19], v[70:71] op_sel_hi:[1,0]
	v_pk_mul_f32 v[16:17], v[16:17], v[70:71] op_sel_hi:[1,0]
	v_pk_mul_f32 v[14:15], v[14:15], v[70:71] op_sel_hi:[1,0]
	v_pk_mul_f32 v[12:13], v[12:13], v[70:71] op_sel_hi:[1,0]
	v_pk_mul_f32 v[10:11], v[10:11], v[70:71] op_sel_hi:[1,0]
	v_pk_mul_f32 v[8:9], v[8:9], v[70:71] op_sel_hi:[1,0]
	v_pk_mul_f32 v[6:7], v[6:7], v[70:71] op_sel_hi:[1,0]
	v_pk_mul_f32 v[4:5], v[4:5], v[70:71] op_sel_hi:[1,0]
	v_pk_mul_f32 v[2:3], v[2:3], v[70:71] op_sel_hi:[1,0]
	v_mul_f32_e32 v153, v153, v70
	v_mov_b32_e32 v69, v68
	v_mov_b32_e32 v70, v68
	v_mov_b32_e32 v71, v68
	v_mov_b32_e32 v72, v68
	v_mov_b32_e32 v73, v68
	v_mov_b32_e32 v74, v68
	v_mov_b32_e32 v75, v68
	v_mov_b32_e32 v76, v68
	v_mov_b32_e32 v77, v68
	v_mov_b32_e32 v78, v68
	v_mov_b32_e32 v79, v68
	v_mov_b32_e32 v80, v68
	v_mov_b32_e32 v81, v68
	v_mov_b32_e32 v82, v68
	v_mov_b32_e32 v83, v68

; #define LAS __attribute__((address_space(3)))
; template <int MODE>
; DI void attn_unit(LAS unsigned char* lds, const bf16_t* Qg, int ldq, const bf16_t* Kg, int ldk, const bf16_t* VTg, int ldvt, bf16_t* Og, int ldo,
;                   int q0, int NT, const float* gout, const float* relb, float lam, float osc, const float* qgain) {
;     ...
;             const LAS unsigned char* Kb = lds + (cur ? KB1 : KB0) + r32 * KSTR + mm * 128 + hi * 16;
;             f32x16 p0, p1;
; #pragma unroll
;             for (int s = 0; s < NS; ++s) { const bf16x8 a0 = *(const LAS bf16x8*)(Kb + s * 32), a1 = *(const LAS bf16x8*)(Kb + 32 * KSTR + s * 32);
;                 if (s == 0) { p0 = MFMA32(a0, qf[0], negm); p1 = MFMA32(a1, qf[0], negm); } else { p0 = MFMA32(a0, qf[s], p0); p1 = MFMA32(a1, qf[s], p1); } }
;             if (MODE != 2) {
;                 if (MODE == 0) {
;                     const int qmin = q0 + 32 * rg;
;                     if (key0 + 63 - qmin > -128) {
;                         const LAS float* tb = (const LAS float*)(lds + TBL) + mm * 320 + (key0 - qrow + 256 + 4 * hi);
; #pragma unroll
;                         for (int i = 0; i < 16; ++i) { p0[i] += tb[(i & 3) + 8 * (i >> 2)]; p1[i] += tb[32 + (i & 3) + 8 * (i >> 2)]; }
;                     }
;                 }
;                 float mx = __builtin_fmaxf(__builtin_fmaxf(p0[0], p0[1]), p0[2]);
; #pragma unroll
;                 for (int i = 3; i < 15; i += 2) mx = __builtin_fmaxf(__builtin_fmaxf(mx, p0[i]), p0[i + 1]);
;                 mx = __builtin_fmaxf(mx, p0[15]);
; #pragma unroll
;                 for (int i = 0; i < 16; i += 2) mx = __builtin_fmaxf(__builtin_fmaxf(mx, p1[i]), p1[i + 1]);
;                 mx = __builtin_fmaxf(mx, shx(mx, 32, lane));
;                 if (t == 0 || __any(mx > 8.f)) {
;                     const float dl = (t == 0) ? mx : __builtin_fmaxf(mx, 0.f);
;                     mhat += dl;
; #pragma unroll
;                     for (int i = 0; i < 16; ++i) { p0[i] -= dl; p1[i] -= dl; }
; #pragma unroll
;                     for (int i = 0; i < 16; ++i) negm[i] = c15 - mhat;
;                     if (t > 0) { const float f = ex2(-dl); lrun *= f;
; #pragma unroll
;                         for (int d = 0; d < NDB; ++d)
; #pragma unroll
;                             for (int i = 0; i < 16; ++i) o[d][i] *= f; }
;                 }
.LBB0_240:
	s_and_b32 s6, s2, 1
	s_cmp_gt_i32 s2, s12
	s_cbranch_scc1 .LBB0_246
	s_cmp_eq_u32 s6, 0
	s_cselect_b32 s2, 0, 0x4400
	v_add_u32_e32 v0, s2, v164
	ds_read_b128 v[6:9], v0 offset:6656
	ds_read_b128 v[10:13], v0
	ds_read_b128 v[144:147], v0 offset:32
	s_mov_b32 s2, 0x41000000
	s_waitcnt lgkmcnt(0)
	v_mfma_f32_32x32x16_bf16 v[64:79], v[6:9], v[124:127], v[48:63]
	ds_read_b128 v[6:9], v0 offset:6688
	v_mfma_f32_32x32x16_bf16 v[80:95], v[10:13], v[124:127], v[48:63]
	v_mfma_f32_32x32x16_bf16 v[80:95], v[144:147], v[116:119], v[80:95]
	s_waitcnt lgkmcnt(0)
	v_mfma_f32_32x32x16_bf16 v[64:79], v[6:9], v[116:119], v[64:79]
	ds_read_b128 v[6:9], v0 offset:6720
	ds_read_b128 v[10:13], v0 offset:64
	s_waitcnt lgkmcnt(0)
	v_mfma_f32_32x32x16_bf16 v[80:95], v[10:13], v[120:123], v[80:95]
	v_mfma_f32_32x32x16_bf16 v[64:79], v[6:9], v[120:123], v[64:79]
	ds_read_b128 v[6:9], v0 offset:6752
	ds_read_b128 v[10:13], v0 offset:96
	s_waitcnt lgkmcnt(0)
	v_mfma_f32_32x32x16_bf16 v[80:95], v[10:13], v[112:115], v[80:95]
	v_mfma_f32_32x32x16_bf16 v[64:79], v[6:9], v[112:115], v[64:79]
	ds_read_b128 v[6:9], v0 offset:6784
	ds_read_b128 v[10:13], v0 offset:128
	s_waitcnt lgkmcnt(0)
	v_mfma_f32_32x32x16_bf16 v[80:95], v[10:13], v[108:111], v[80:95]
	v_mfma_f32_32x32x16_bf16 v[64:79], v[6:9], v[108:111], v[64:79]
	ds_read_b128 v[6:9], v0 offset:6816
	ds_read_b128 v[10:13], v0 offset:160
	s_waitcnt lgkmcnt(0)
	v_mfma_f32_32x32x16_bf16 v[80:95], v[10:13], v[104:107], v[80:95]
	v_mfma_f32_32x32x16_bf16 v[64:79], v[6:9], v[104:107], v[64:79]
	s_nop 10
	v_max_f32_e32 v0, v80, v81
	v_max3_f32 v0, v0, v82, v83
	v_max3_f32 v0, v0, v84, v85
	v_max3_f32 v0, v0, v86, v87
	v_max3_f32 v0, v0, v88, v89
	v_max3_f32 v0, v0, v90, v91
	v_max3_f32 v0, v0, v92, v93
	v_max3_f32 v0, v0, v94, v95
	v_max3_f32 v0, v0, v64, v65
	v_max3_f32 v0, v0, v66, v67
	v_max3_f32 v0, v0, v68, v69
	v_max3_f32 v0, v0, v70, v71
	v_max3_f32 v0, v0, v72, v73
	v_max3_f32 v0, v0, v74, v75
	v_max3_f32 v0, v0, v76, v77
	v_max3_f32 v0, v0, v78, v79
	v_mov_b32_e32 v6, v0
	v_mov_b32_e32 v7, v0
	s_nop 1
	v_permlane32_swap_b32_e32 v6, v7
	v_max3_f32 v0, v0, v6, v7
	v_cmp_lt_f32_e32 vcc, s2, v0
	s_cbranch_vccz .LBB0_243
	v_max_f32_e32 v0, v0, v0
	v_max_f32_e32 v0, 0, v0
	v_pk_add_f32 v[64:65], v[64:65], v[0:1] op_sel_hi:[1,0] neg_lo:[0,1] neg_hi:[0,1]
	v_pk_add_f32 v[66:67], v[66:67], v[0:1] op_sel_hi:[1,0] neg_lo:[0,1] neg_hi:[0,1]
	v_pk_add_f32 v[68:69], v[68:69], v[0:1] op_sel_hi:[1,0] neg_lo:[0,1] neg_hi:[0,1]
	v_pk_add_f32 v[70:71], v[70:71], v[0:1] op_sel_hi:[1,0] neg_lo:[0,1] neg_hi:[0,1]
	v_pk_add_f32 v[72:73], v[72:73], v[0:1] op_sel_hi:[1,0] neg_lo:[0,1] neg_hi:[0,1]
	v_pk_add_f32 v[74:75], v[74:75], v[0:1] op_sel_hi:[1,0] neg_lo:[0,1] neg_hi:[0,1]
	v_pk_add_f32 v[76:77], v[76:77], v[0:1] op_sel_hi:[1,0] neg_lo:[0,1] neg_hi:[0,1]
	v_pk_add_f32 v[78:79], v[78:79], v[0:1] op_sel_hi:[1,0] neg_lo:[0,1] neg_hi:[0,1]
	v_pk_add_f32 v[80:81], v[80:81], v[0:1] op_sel_hi:[1,0] neg_lo:[0,1] neg_hi:[0,1]
	v_pk_add_f32 v[82:83], v[82:83], v[0:1] op_sel_hi:[1,0] neg_lo:[0,1] neg_hi:[0,1]
	v_pk_add_f32 v[84:85], v[84:85], v[0:1] op_sel_hi:[1,0] neg_lo:[0,1] neg_hi:[0,1]
	v_pk_add_f32 v[86:87], v[86:87], v[0:1] op_sel_hi:[1,0] neg_lo:[0,1] neg_hi:[0,1]
	v_pk_add_f32 v[88:89], v[88:89], v[0:1] op_sel_hi:[1,0] neg_lo:[0,1] neg_hi:[0,1]
	v_pk_add_f32 v[90:91], v[90:91], v[0:1] op_sel_hi:[1,0] neg_lo:[0,1] neg_hi:[0,1]
	v_pk_add_f32 v[92:93], v[92:93], v[0:1] op_sel_hi:[1,0] neg_lo:[0,1] neg_hi:[0,1]
	v_pk_add_f32 v[94:95], v[94:95], v[0:1] op_sel_hi:[1,0] neg_lo:[0,1] neg_hi:[0,1]
	v_add_f32_e32 v132, v132, v0
	v_exp_f32_e64 v0, -v0
	v_sub_f32_e32 v48, 0, v132
	v_mov_b32_e32 v49, v48
	v_mov_b32_e32 v50, v48
	v_mov_b32_e32 v51, v48
	v_mov_b32_e32 v52, v48
	v_mov_b32_e32 v53, v48
	v_mov_b32_e32 v54, v48
	v_mov_b32_e32 v55, v48
	v_mov_b32_e32 v56, v48
	v_mov_b32_e32 v57, v48
	v_mov_b32_e32 v58, v48
	v_mov_b32_e32 v59, v48
	v_mov_b32_e32 v60, v48
	v_mov_b32_e32 v61, v48
	v_mov_b32_e32 v62, v48
	v_mov_b32_e32 v63, v48
	v_pk_mul_f32 v[46:47], v[46:47], v[0:1] op_sel_hi:[1,0]
	v_pk_mul_f32 v[44:45], v[44:45], v[0:1] op_sel_hi:[1,0]
	v_pk_mul_f32 v[42:43], v[42:43], v[0:1] op_sel_hi:[1,0]
	v_pk_mul_f32 v[40:41], v[40:41], v[0:1] op_sel_hi:[1,0]
	v_pk_mul_f32 v[38:39], v[38:39], v[0:1] op_sel_hi:[1,0]
	v_pk_mul_f32 v[36:37], v[36:37], v[0:1] op_sel_hi:[1,0]
	v_pk_mul_f32 v[34:35], v[34:35], v[0:1] op_sel_hi:[1,0]
	v_pk_mul_f32 v[32:33], v[32:33], v[0:1] op_sel_hi:[1,0]
	v_pk_mul_f32 v[30:31], v[30:31], v[0:1] op_sel_hi:[1,0]
	v_pk_mul_f32 v[28:29], v[28:29], v[0:1] op_sel_hi:[1,0]
	v_pk_mul_f32 v[26:27], v[26:27], v[0:1] op_sel_hi:[1,0]
	v_pk_mul_f32 v[24:25], v[24:25], v[0:1] op_sel_hi:[1,0]
	v_pk_mul_f32 v[22:23], v[22:23], v[0:1] op_sel_hi:[1,0]
	v_pk_mul_f32 v[20:21], v[20:21], v[0:1] op_sel_hi:[1,0]
	v_pk_mul_f32 v[18:19], v[18:19], v[0:1] op_sel_hi:[1,0]
	v_pk_mul_f32 v[16:17], v[16:17], v[0:1] op_sel_hi:[1,0]
	v_mul_f32_e32 v133, v133, v0
